# SWIGLU epilogue re-generated: per-row scale folded (49 instead of 73 instructions per row), 4 pairs interleaved
# speedup vs baseline: 1.0098x; 1.0060x over previous
; __device__ __forceinline__ unsigned cvtpk(float lo, float hi) { f32x2_t v = {lo, hi}; bf16x2_t b = __builtin_convertvector(v, bf16x2_t); return __builtin_bit_cast(unsigned, b); }
; __device__ __forceinline__ float bf_lo(unsigned w) { return __uint_as_float(w << 16); }
; __device__ __forceinline__ float bf_hi(unsigned w) { return __uint_as_float(w & 0xffff0000u); }
; __device__ __forceinline__ float sigm_f(float v) { return __builtin_amdgcn_rcpf(1.0f + __builtin_amdgcn_exp2f(-1.44269504f * v)); }
; __device__ __forceinline__ float silu_f(float v) { return v * sigm_f(v); }
; __device__ __forceinline__ void store8(bf16_t* p, const f32x4 a, const f32x4 b) {
;     u32x4 w; w.x = cvtpk(a[0], a[1]); w.y = cvtpk(a[2], a[3]); w.z = cvtpk(b[0], b[1]); w.w = cvtpk(b[2], b[3]); *(u32x4*)p = w;
; }
;     __device__ __forceinline__ void operator()(const f32x4 (&acc)[2][2][4][2], const Unit& u, int wr, int wc, int fr, int fq) const {
;     ...
;                 for (int m = 0; m < 4; ++m) { const int row = row0 + ai * HALF + m * 16; const float rsv = __builtin_amdgcn_rsqf(rs[row] * (1.0f / 1024.0f) + 1e-6f);
;                     f32x4 h0, h1;
; #pragma unroll
;                     for (int e = 0; e < 4; ++e) { h0[e] = silu_f(acc[ai][0][m][0][e] * rsv) * (acc[ai][1][m][0][e] * rsv); h1[e] = silu_f(acc[ai][0][m][1][e] * rsv) * (acc[ai][1][m][1][e] * rsv); }
;                     store8(O + (size_t)row * ldc + u.pn * HALF + cw, h0, h1); }
.LBB0_588:
	s_mov_b64 s[6:7], -1
	s_cmp_lt_i32 s37, 1
	v_lshlrev_b64 v[128:129], 1, v[148:149]
	v_or_b32_e32 v171, 16, v164
	v_or_b32_e32 v170, 32, v164
	v_or_b32_e32 v169, 48, v164
	v_add_u32_e32 v168, 0x80, v164
	v_add_u32_e32 v167, 0x90, v164
	v_add_u32_e32 v166, 0xa0, v164
	s_cbranch_scc1 .LBB0_590
	v_ashrrev_i32_e32 v165, 31, v164
	v_lshl_add_u64 v[130:131], v[164:165], 2, s[26:27]
	global_load_dword v246, v[130:131], off
	global_load_dword v247, v[130:131], off offset:64
	global_load_dword v248, v[130:131], off offset:128
	global_load_dword v249, v[130:131], off offset:192
	global_load_dword v250, v[130:131], off offset:512
	global_load_dword v252, v[130:131], off offset:576
	global_load_dword v253, v[130:131], off offset:640
	global_load_dword v255, v[130:131], off offset:704
	s_lshl_b32 s6, s40, 7
	s_ashr_i32 s7, s6, 31
	s_lshl_b64 s[6:7], s[6:7], 1
	v_add_u32_e32 v165, 0xb0, v164
	s_waitcnt vmcnt(0) lgkmcnt(0)
	v_mov_b32_e32 v188, 1.0
	v_mov_b32_e32 v189, 1.0
	v_fmamk_f32 v206, v246, 0x3a800000, v237
	v_rsq_f32_e32 v182, v206
	v_mad_i64_i32 v[172:173], s[38:39], s82, v164, 0
	v_lshl_add_u64 v[172:173], v[172:173], 1, s[84:85]
	v_lshl_add_u64 v[172:173], v[172:173], 0, s[6:7]
	v_lshl_add_u64 v[172:173], v[172:173], 0, v[128:129]
	v_mul_f32_e32 v184, 0xbfb8aa3b, v182
	v_mul_f32_e32 v186, v182, v182
	v_pk_mul_f32 v[190:191], v[124:125], v[184:185] op_sel_hi:[1,0]
	v_pk_mul_f32 v[192:193], v[126:127], v[184:185] op_sel_hi:[1,0]
	v_pk_mul_f32 v[194:195], v[120:121], v[184:185] op_sel_hi:[1,0]
	v_pk_mul_f32 v[196:197], v[122:123], v[184:185] op_sel_hi:[1,0]
	v_exp_f32_e32 v190, v190
	v_exp_f32_e32 v191, v191
	v_exp_f32_e32 v192, v192
	v_exp_f32_e32 v193, v193
	v_exp_f32_e32 v194, v194
	v_exp_f32_e32 v195, v195
	v_exp_f32_e32 v196, v196
	v_exp_f32_e32 v197, v197
	v_pk_mul_f32 v[198:199], v[124:125], v[108:109]
	v_pk_mul_f32 v[200:201], v[126:127], v[110:111]
	v_pk_mul_f32 v[202:203], v[120:121], v[104:105]
	v_pk_mul_f32 v[204:205], v[122:123], v[106:107]
	v_pk_add_f32 v[190:191], v[190:191], v[188:189]
	v_pk_add_f32 v[192:193], v[192:193], v[188:189]
	v_pk_add_f32 v[194:195], v[194:195], v[188:189]
	v_pk_add_f32 v[196:197], v[196:197], v[188:189]
	v_rcp_f32_e32 v190, v190
	v_rcp_f32_e32 v191, v191
	v_rcp_f32_e32 v192, v192
	v_rcp_f32_e32 v193, v193
	v_rcp_f32_e32 v194, v194
	v_rcp_f32_e32 v195, v195
	v_rcp_f32_e32 v196, v196
	v_rcp_f32_e32 v197, v197
	v_pk_mul_f32 v[198:199], v[198:199], v[186:187] op_sel_hi:[1,0]
	v_pk_mul_f32 v[200:201], v[200:201], v[186:187] op_sel_hi:[1,0]
	v_pk_mul_f32 v[202:203], v[202:203], v[186:187] op_sel_hi:[1,0]
	v_pk_mul_f32 v[204:205], v[204:205], v[186:187] op_sel_hi:[1,0]
	v_pk_mul_f32 v[198:199], v[198:199], v[190:191]
	v_pk_mul_f32 v[200:201], v[200:201], v[192:193]
	v_pk_mul_f32 v[202:203], v[202:203], v[194:195]
	v_pk_mul_f32 v[204:205], v[204:205], v[196:197]
	v_cvt_pk_bf16_f32 v132, v198, v199
	v_cvt_pk_bf16_f32 v133, v200, v201
	v_cvt_pk_bf16_f32 v134, v202, v203
	v_cvt_pk_bf16_f32 v135, v204, v205
	flat_store_dwordx4 v[172:173], v[132:135]
	v_fmamk_f32 v206, v247, 0x3a800000, v237
	v_rsq_f32_e32 v182, v206
	v_mad_i64_i32 v[172:173], s[38:39], s82, v171, 0
	v_lshl_add_u64 v[172:173], v[172:173], 1, s[84:85]
	v_lshl_add_u64 v[172:173], v[172:173], 0, s[6:7]
	v_lshl_add_u64 v[172:173], v[172:173], 0, v[128:129]
	v_mul_f32_e32 v184, 0xbfb8aa3b, v182
	v_mul_f32_e32 v186, v182, v182
	v_pk_mul_f32 v[190:191], v[116:117], v[184:185] op_sel_hi:[1,0]
	v_pk_mul_f32 v[192:193], v[118:119], v[184:185] op_sel_hi:[1,0]
	v_pk_mul_f32 v[194:195], v[112:113], v[184:185] op_sel_hi:[1,0]
	v_pk_mul_f32 v[196:197], v[114:115], v[184:185] op_sel_hi:[1,0]
	v_exp_f32_e32 v190, v190
	v_exp_f32_e32 v191, v191
	v_exp_f32_e32 v192, v192
	v_exp_f32_e32 v193, v193
	v_exp_f32_e32 v194, v194
	v_exp_f32_e32 v195, v195
	v_exp_f32_e32 v196, v196
	v_exp_f32_e32 v197, v197
	v_pk_mul_f32 v[198:199], v[116:117], v[92:93]
	v_pk_mul_f32 v[200:201], v[118:119], v[94:95]
	v_pk_mul_f32 v[202:203], v[112:113], v[88:89]
	v_pk_mul_f32 v[204:205], v[114:115], v[90:91]
	v_pk_add_f32 v[190:191], v[190:191], v[188:189]
	v_pk_add_f32 v[192:193], v[192:193], v[188:189]
	v_pk_add_f32 v[194:195], v[194:195], v[188:189]
	v_pk_add_f32 v[196:197], v[196:197], v[188:189]
	v_rcp_f32_e32 v190, v190
	v_rcp_f32_e32 v191, v191
	v_rcp_f32_e32 v192, v192
	v_rcp_f32_e32 v193, v193
	v_rcp_f32_e32 v194, v194
	v_rcp_f32_e32 v195, v195
	v_rcp_f32_e32 v196, v196
	v_rcp_f32_e32 v197, v197
	v_pk_mul_f32 v[198:199], v[198:199], v[186:187] op_sel_hi:[1,0]
	v_pk_mul_f32 v[200:201], v[200:201], v[186:187] op_sel_hi:[1,0]
	v_pk_mul_f32 v[202:203], v[202:203], v[186:187] op_sel_hi:[1,0]
	v_pk_mul_f32 v[204:205], v[204:205], v[186:187] op_sel_hi:[1,0]
	v_pk_mul_f32 v[198:199], v[198:199], v[190:191]
	v_pk_mul_f32 v[200:201], v[200:201], v[192:193]
	v_pk_mul_f32 v[202:203], v[202:203], v[194:195]
	v_pk_mul_f32 v[204:205], v[204:205], v[196:197]
	v_cvt_pk_bf16_f32 v132, v198, v199
	v_cvt_pk_bf16_f32 v133, v200, v201
	v_cvt_pk_bf16_f32 v134, v202, v203
	v_cvt_pk_bf16_f32 v135, v204, v205
	flat_store_dwordx4 v[172:173], v[132:135]
	v_fmamk_f32 v206, v248, 0x3a800000, v237
	v_rsq_f32_e32 v182, v206
	v_mad_i64_i32 v[172:173], s[38:39], s82, v170, 0
	v_lshl_add_u64 v[172:173], v[172:173], 1, s[84:85]
	v_lshl_add_u64 v[172:173], v[172:173], 0, s[6:7]
	v_lshl_add_u64 v[172:173], v[172:173], 0, v[128:129]
	v_mul_f32_e32 v184, 0xbfb8aa3b, v182
	v_mul_f32_e32 v186, v182, v182
	v_pk_mul_f32 v[190:191], v[100:101], v[184:185] op_sel_hi:[1,0]
	v_pk_mul_f32 v[192:193], v[102:103], v[184:185] op_sel_hi:[1,0]
	v_pk_mul_f32 v[194:195], v[96:97], v[184:185] op_sel_hi:[1,0]
; __device__ __forceinline__ unsigned cvtpk(float lo, float hi) { f32x2_t v = {lo, hi}; bf16x2_t b = __builtin_convertvector(v, bf16x2_t); return __builtin_bit_cast(unsigned, b); }
; __device__ __forceinline__ float bf_lo(unsigned w) { return __uint_as_float(w << 16); }
; __device__ __forceinline__ float bf_hi(unsigned w) { return __uint_as_float(w & 0xffff0000u); }
; __device__ __forceinline__ float sigm_f(float v) { return __builtin_amdgcn_rcpf(1.0f + __builtin_amdgcn_exp2f(-1.44269504f * v)); }
; __device__ __forceinline__ float silu_f(float v) { return v * sigm_f(v); }
; __device__ __forceinline__ void store8(bf16_t* p, const f32x4 a, const f32x4 b) {
;     u32x4 w; w.x = cvtpk(a[0], a[1]); w.y = cvtpk(a[2], a[3]); w.z = cvtpk(b[0], b[1]); w.w = cvtpk(b[2], b[3]); *(u32x4*)p = w;
; }
;     __device__ __forceinline__ void operator()(const f32x4 (&acc)[2][2][4][2], const Unit& u, int wr, int wc, int fr, int fq) const {
;     ...
;                 for (int m = 0; m < 4; ++m) { const int row = row0 + ai * HALF + m * 16; const float rsv = __builtin_amdgcn_rsqf(rs[row] * (1.0f / 1024.0f) + 1e-6f);
;                     f32x4 h0, h1;
; #pragma unroll
;                     for (int e = 0; e < 4; ++e) { h0[e] = silu_f(acc[ai][0][m][0][e] * rsv) * (acc[ai][1][m][0][e] * rsv); h1[e] = silu_f(acc[ai][0][m][1][e] * rsv) * (acc[ai][1][m][1][e] * rsv); }
;                     store8(O + (size_t)row * ldc + u.pn * HALF + cw, h0, h1); }
	v_pk_mul_f32 v[196:197], v[98:99], v[184:185] op_sel_hi:[1,0]
	v_exp_f32_e32 v190, v190
	v_exp_f32_e32 v191, v191
	v_exp_f32_e32 v192, v192
	v_exp_f32_e32 v193, v193
	v_exp_f32_e32 v194, v194
	v_exp_f32_e32 v195, v195
	v_exp_f32_e32 v196, v196
	v_exp_f32_e32 v197, v197
	v_pk_mul_f32 v[198:199], v[100:101], v[76:77]
	v_pk_mul_f32 v[200:201], v[102:103], v[78:79]
	v_pk_mul_f32 v[202:203], v[96:97], v[72:73]
	v_pk_mul_f32 v[204:205], v[98:99], v[74:75]
	v_pk_add_f32 v[190:191], v[190:191], v[188:189]
	v_pk_add_f32 v[192:193], v[192:193], v[188:189]
	v_pk_add_f32 v[194:195], v[194:195], v[188:189]
	v_pk_add_f32 v[196:197], v[196:197], v[188:189]
	v_rcp_f32_e32 v190, v190
	v_rcp_f32_e32 v191, v191
	v_rcp_f32_e32 v192, v192
	v_rcp_f32_e32 v193, v193
	v_rcp_f32_e32 v194, v194
	v_rcp_f32_e32 v195, v195
	v_rcp_f32_e32 v196, v196
	v_rcp_f32_e32 v197, v197
	v_pk_mul_f32 v[198:199], v[198:199], v[186:187] op_sel_hi:[1,0]
	v_pk_mul_f32 v[200:201], v[200:201], v[186:187] op_sel_hi:[1,0]
	v_pk_mul_f32 v[202:203], v[202:203], v[186:187] op_sel_hi:[1,0]
	v_pk_mul_f32 v[204:205], v[204:205], v[186:187] op_sel_hi:[1,0]
	v_pk_mul_f32 v[198:199], v[198:199], v[190:191]
	v_pk_mul_f32 v[200:201], v[200:201], v[192:193]
	v_pk_mul_f32 v[202:203], v[202:203], v[194:195]
	v_pk_mul_f32 v[204:205], v[204:205], v[196:197]
	v_cvt_pk_bf16_f32 v132, v198, v199
	v_cvt_pk_bf16_f32 v133, v200, v201
	v_cvt_pk_bf16_f32 v134, v202, v203
	v_cvt_pk_bf16_f32 v135, v204, v205
	flat_store_dwordx4 v[172:173], v[132:135]
	v_fmamk_f32 v206, v249, 0x3a800000, v237
	v_rsq_f32_e32 v182, v206
	v_mad_i64_i32 v[172:173], s[38:39], s82, v169, 0
	v_lshl_add_u64 v[172:173], v[172:173], 1, s[84:85]
	v_lshl_add_u64 v[172:173], v[172:173], 0, s[6:7]
	v_lshl_add_u64 v[172:173], v[172:173], 0, v[128:129]
	v_mul_f32_e32 v184, 0xbfb8aa3b, v182
	v_mul_f32_e32 v186, v182, v182
	v_pk_mul_f32 v[190:191], v[84:85], v[184:185] op_sel_hi:[1,0]
	v_pk_mul_f32 v[192:193], v[86:87], v[184:185] op_sel_hi:[1,0]
	v_pk_mul_f32 v[194:195], v[80:81], v[184:185] op_sel_hi:[1,0]
	v_pk_mul_f32 v[196:197], v[82:83], v[184:185] op_sel_hi:[1,0]
	v_exp_f32_e32 v190, v190
	v_exp_f32_e32 v191, v191
	v_exp_f32_e32 v192, v192
	v_exp_f32_e32 v193, v193
	v_exp_f32_e32 v194, v194
	v_exp_f32_e32 v195, v195
	v_exp_f32_e32 v196, v196
	v_exp_f32_e32 v197, v197
	v_pk_mul_f32 v[198:199], v[84:85], v[68:69]
	v_pk_mul_f32 v[200:201], v[86:87], v[70:71]
	v_pk_mul_f32 v[202:203], v[80:81], v[64:65]
	v_pk_mul_f32 v[204:205], v[82:83], v[66:67]
	v_pk_add_f32 v[190:191], v[190:191], v[188:189]
	v_pk_add_f32 v[192:193], v[192:193], v[188:189]
	v_pk_add_f32 v[194:195], v[194:195], v[188:189]
	v_pk_add_f32 v[196:197], v[196:197], v[188:189]
	v_rcp_f32_e32 v190, v190
	v_rcp_f32_e32 v191, v191
	v_rcp_f32_e32 v192, v192
	v_rcp_f32_e32 v193, v193
	v_rcp_f32_e32 v194, v194
	v_rcp_f32_e32 v195, v195
	v_rcp_f32_e32 v196, v196
	v_rcp_f32_e32 v197, v197
	v_pk_mul_f32 v[198:199], v[198:199], v[186:187] op_sel_hi:[1,0]
	v_pk_mul_f32 v[200:201], v[200:201], v[186:187] op_sel_hi:[1,0]
	v_pk_mul_f32 v[202:203], v[202:203], v[186:187] op_sel_hi:[1,0]
	v_pk_mul_f32 v[204:205], v[204:205], v[186:187] op_sel_hi:[1,0]
	v_pk_mul_f32 v[198:199], v[198:199], v[190:191]
	v_pk_mul_f32 v[200:201], v[200:201], v[192:193]
	v_pk_mul_f32 v[202:203], v[202:203], v[194:195]
	v_pk_mul_f32 v[204:205], v[204:205], v[196:197]
	v_cvt_pk_bf16_f32 v132, v198, v199
	v_cvt_pk_bf16_f32 v133, v200, v201
	v_cvt_pk_bf16_f32 v134, v202, v203
	v_cvt_pk_bf16_f32 v135, v204, v205
	flat_store_dwordx4 v[172:173], v[132:135]
	v_fmamk_f32 v206, v250, 0x3a800000, v237
	v_rsq_f32_e32 v182, v206
	v_mad_i64_i32 v[172:173], s[38:39], s82, v168, 0
	v_lshl_add_u64 v[172:173], v[172:173], 1, s[84:85]
	v_lshl_add_u64 v[172:173], v[172:173], 0, s[6:7]
	v_lshl_add_u64 v[172:173], v[172:173], 0, v[128:129]
	v_mul_f32_e32 v184, 0xbfb8aa3b, v182
	v_mul_f32_e32 v186, v182, v182
	v_pk_mul_f32 v[190:191], v[60:61], v[184:185] op_sel_hi:[1,0]
	v_pk_mul_f32 v[192:193], v[62:63], v[184:185] op_sel_hi:[1,0]
	v_pk_mul_f32 v[194:195], v[56:57], v[184:185] op_sel_hi:[1,0]
	v_pk_mul_f32 v[196:197], v[58:59], v[184:185] op_sel_hi:[1,0]
	v_exp_f32_e32 v190, v190
	v_exp_f32_e32 v191, v191
	v_exp_f32_e32 v192, v192
	v_exp_f32_e32 v193, v193
	v_exp_f32_e32 v194, v194
	v_exp_f32_e32 v195, v195
	v_exp_f32_e32 v196, v196
	v_exp_f32_e32 v197, v197
	v_pk_mul_f32 v[198:199], v[60:61], v[44:45]
	v_pk_mul_f32 v[200:201], v[62:63], v[46:47]
	v_pk_mul_f32 v[202:203], v[56:57], v[40:41]
	v_pk_mul_f32 v[204:205], v[58:59], v[42:43]
	v_pk_add_f32 v[190:191], v[190:191], v[188:189]
	v_pk_add_f32 v[192:193], v[192:193], v[188:189]
	v_pk_add_f32 v[194:195], v[194:195], v[188:189]
	v_pk_add_f32 v[196:197], v[196:197], v[188:189]
	v_rcp_f32_e32 v190, v190
	v_rcp_f32_e32 v191, v191
	v_rcp_f32_e32 v192, v192
	v_rcp_f32_e32 v193, v193
	v_rcp_f32_e32 v194, v194
	v_rcp_f32_e32 v195, v195
	v_rcp_f32_e32 v196, v196
	v_rcp_f32_e32 v197, v197
	v_pk_mul_f32 v[198:199], v[198:199], v[186:187] op_sel_hi:[1,0]
	v_pk_mul_f32 v[200:201], v[200:201], v[186:187] op_sel_hi:[1,0]
	v_pk_mul_f32 v[202:203], v[202:203], v[186:187] op_sel_hi:[1,0]
	v_pk_mul_f32 v[204:205], v[204:205], v[186:187] op_sel_hi:[1,0]
	v_pk_mul_f32 v[198:199], v[198:199], v[190:191]
	v_pk_mul_f32 v[200:201], v[200:201], v[192:193]
	v_pk_mul_f32 v[202:203], v[202:203], v[194:195]
	v_pk_mul_f32 v[204:205], v[204:205], v[196:197]
	v_cvt_pk_bf16_f32 v132, v198, v199
	v_cvt_pk_bf16_f32 v133, v200, v201
	v_cvt_pk_bf16_f32 v134, v202, v203
	v_cvt_pk_bf16_f32 v135, v204, v205
	flat_store_dwordx4 v[172:173], v[132:135]
	v_fmamk_f32 v206, v252, 0x3a800000, v237
	v_rsq_f32_e32 v182, v206
; __device__ __forceinline__ unsigned cvtpk(float lo, float hi) { f32x2_t v = {lo, hi}; bf16x2_t b = __builtin_convertvector(v, bf16x2_t); return __builtin_bit_cast(unsigned, b); }
; __device__ __forceinline__ float bf_lo(unsigned w) { return __uint_as_float(w << 16); }
; __device__ __forceinline__ float bf_hi(unsigned w) { return __uint_as_float(w & 0xffff0000u); }
; __device__ __forceinline__ float sigm_f(float v) { return __builtin_amdgcn_rcpf(1.0f + __builtin_amdgcn_exp2f(-1.44269504f * v)); }
; __device__ __forceinline__ float silu_f(float v) { return v * sigm_f(v); }
; __device__ __forceinline__ void store8(bf16_t* p, const f32x4 a, const f32x4 b) {
;     u32x4 w; w.x = cvtpk(a[0], a[1]); w.y = cvtpk(a[2], a[3]); w.z = cvtpk(b[0], b[1]); w.w = cvtpk(b[2], b[3]); *(u32x4*)p = w;
; }
;     __device__ __forceinline__ void operator()(const f32x4 (&acc)[2][2][4][2], const Unit& u, int wr, int wc, int fr, int fq) const {
;     ...
;                 for (int m = 0; m < 4; ++m) { const int row = row0 + ai * HALF + m * 16; const float rsv = __builtin_amdgcn_rsqf(rs[row] * (1.0f / 1024.0f) + 1e-6f);
;                     f32x4 h0, h1;
; #pragma unroll
;                     for (int e = 0; e < 4; ++e) { h0[e] = silu_f(acc[ai][0][m][0][e] * rsv) * (acc[ai][1][m][0][e] * rsv); h1[e] = silu_f(acc[ai][0][m][1][e] * rsv) * (acc[ai][1][m][1][e] * rsv); }
;                     store8(O + (size_t)row * ldc + u.pn * HALF + cw, h0, h1); }
	v_mad_i64_i32 v[172:173], s[38:39], s82, v167, 0
	v_lshl_add_u64 v[172:173], v[172:173], 1, s[84:85]
	v_lshl_add_u64 v[172:173], v[172:173], 0, s[6:7]
	v_lshl_add_u64 v[172:173], v[172:173], 0, v[128:129]
	v_mul_f32_e32 v184, 0xbfb8aa3b, v182
	v_mul_f32_e32 v186, v182, v182
	v_pk_mul_f32 v[190:191], v[52:53], v[184:185] op_sel_hi:[1,0]
	v_pk_mul_f32 v[192:193], v[54:55], v[184:185] op_sel_hi:[1,0]
	v_pk_mul_f32 v[194:195], v[48:49], v[184:185] op_sel_hi:[1,0]
	v_pk_mul_f32 v[196:197], v[50:51], v[184:185] op_sel_hi:[1,0]
	v_exp_f32_e32 v190, v190
	v_exp_f32_e32 v191, v191
	v_exp_f32_e32 v192, v192
	v_exp_f32_e32 v193, v193
	v_exp_f32_e32 v194, v194
	v_exp_f32_e32 v195, v195
	v_exp_f32_e32 v196, v196
	v_exp_f32_e32 v197, v197
	v_pk_mul_f32 v[198:199], v[52:53], v[28:29]
	v_pk_mul_f32 v[200:201], v[54:55], v[30:31]
	v_pk_mul_f32 v[202:203], v[48:49], v[24:25]
	v_pk_mul_f32 v[204:205], v[50:51], v[26:27]
	v_pk_add_f32 v[190:191], v[190:191], v[188:189]
	v_pk_add_f32 v[192:193], v[192:193], v[188:189]
	v_pk_add_f32 v[194:195], v[194:195], v[188:189]
	v_pk_add_f32 v[196:197], v[196:197], v[188:189]
	v_rcp_f32_e32 v190, v190
	v_rcp_f32_e32 v191, v191
	v_rcp_f32_e32 v192, v192
	v_rcp_f32_e32 v193, v193
	v_rcp_f32_e32 v194, v194
	v_rcp_f32_e32 v195, v195
	v_rcp_f32_e32 v196, v196
	v_rcp_f32_e32 v197, v197
	v_pk_mul_f32 v[198:199], v[198:199], v[186:187] op_sel_hi:[1,0]
	v_pk_mul_f32 v[200:201], v[200:201], v[186:187] op_sel_hi:[1,0]
	v_pk_mul_f32 v[202:203], v[202:203], v[186:187] op_sel_hi:[1,0]
	v_pk_mul_f32 v[204:205], v[204:205], v[186:187] op_sel_hi:[1,0]
	v_pk_mul_f32 v[198:199], v[198:199], v[190:191]
	v_pk_mul_f32 v[200:201], v[200:201], v[192:193]
	v_pk_mul_f32 v[202:203], v[202:203], v[194:195]
	v_pk_mul_f32 v[204:205], v[204:205], v[196:197]
	v_cvt_pk_bf16_f32 v132, v198, v199
	v_cvt_pk_bf16_f32 v133, v200, v201
	v_cvt_pk_bf16_f32 v134, v202, v203
	v_cvt_pk_bf16_f32 v135, v204, v205
	flat_store_dwordx4 v[172:173], v[132:135]
	v_fmamk_f32 v206, v253, 0x3a800000, v237
	v_rsq_f32_e32 v182, v206
	v_mad_i64_i32 v[172:173], s[38:39], s82, v166, 0
	v_lshl_add_u64 v[172:173], v[172:173], 1, s[84:85]
	v_lshl_add_u64 v[172:173], v[172:173], 0, s[6:7]
	v_lshl_add_u64 v[172:173], v[172:173], 0, v[128:129]
	v_mul_f32_e32 v184, 0xbfb8aa3b, v182
	v_mul_f32_e32 v186, v182, v182
	v_pk_mul_f32 v[190:191], v[36:37], v[184:185] op_sel_hi:[1,0]
	v_pk_mul_f32 v[192:193], v[38:39], v[184:185] op_sel_hi:[1,0]
	v_pk_mul_f32 v[194:195], v[32:33], v[184:185] op_sel_hi:[1,0]
	v_pk_mul_f32 v[196:197], v[34:35], v[184:185] op_sel_hi:[1,0]
	v_exp_f32_e32 v190, v190
	v_exp_f32_e32 v191, v191
	v_exp_f32_e32 v192, v192
	v_exp_f32_e32 v193, v193
	v_exp_f32_e32 v194, v194
	v_exp_f32_e32 v195, v195
	v_exp_f32_e32 v196, v196
	v_exp_f32_e32 v197, v197
	v_pk_mul_f32 v[198:199], v[36:37], v[12:13]
	v_pk_mul_f32 v[200:201], v[38:39], v[14:15]
	v_pk_mul_f32 v[202:203], v[32:33], v[8:9]
	v_pk_mul_f32 v[204:205], v[34:35], v[10:11]
	v_pk_add_f32 v[190:191], v[190:191], v[188:189]
	v_pk_add_f32 v[192:193], v[192:193], v[188:189]
	v_pk_add_f32 v[194:195], v[194:195], v[188:189]
	v_pk_add_f32 v[196:197], v[196:197], v[188:189]
	v_rcp_f32_e32 v190, v190
	v_rcp_f32_e32 v191, v191
	v_rcp_f32_e32 v192, v192
	v_rcp_f32_e32 v193, v193
	v_rcp_f32_e32 v194, v194
	v_rcp_f32_e32 v195, v195
	v_rcp_f32_e32 v196, v196
	v_rcp_f32_e32 v197, v197
	v_pk_mul_f32 v[198:199], v[198:199], v[186:187] op_sel_hi:[1,0]
	v_pk_mul_f32 v[200:201], v[200:201], v[186:187] op_sel_hi:[1,0]
	v_pk_mul_f32 v[202:203], v[202:203], v[186:187] op_sel_hi:[1,0]
	v_pk_mul_f32 v[204:205], v[204:205], v[186:187] op_sel_hi:[1,0]
	v_pk_mul_f32 v[198:199], v[198:199], v[190:191]
	v_pk_mul_f32 v[200:201], v[200:201], v[192:193]
	v_pk_mul_f32 v[202:203], v[202:203], v[194:195]
	v_pk_mul_f32 v[204:205], v[204:205], v[196:197]
	v_cvt_pk_bf16_f32 v132, v198, v199
	v_cvt_pk_bf16_f32 v133, v200, v201
	v_cvt_pk_bf16_f32 v134, v202, v203
	v_cvt_pk_bf16_f32 v135, v204, v205
	flat_store_dwordx4 v[172:173], v[132:135]
	v_fmamk_f32 v206, v255, 0x3a800000, v237
	v_rsq_f32_e32 v182, v206
	v_mad_i64_i32 v[172:173], s[38:39], s82, v165, 0
	v_lshl_add_u64 v[172:173], v[172:173], 1, s[84:85]
	v_lshl_add_u64 v[172:173], v[172:173], 0, s[6:7]
	v_lshl_add_u64 v[172:173], v[172:173], 0, v[128:129]
	v_mul_f32_e32 v184, 0xbfb8aa3b, v182
	v_mul_f32_e32 v186, v182, v182
	v_pk_mul_f32 v[190:191], v[20:21], v[184:185] op_sel_hi:[1,0]
	v_pk_mul_f32 v[192:193], v[22:23], v[184:185] op_sel_hi:[1,0]
	v_pk_mul_f32 v[194:195], v[16:17], v[184:185] op_sel_hi:[1,0]
	v_pk_mul_f32 v[196:197], v[18:19], v[184:185] op_sel_hi:[1,0]
	v_exp_f32_e32 v190, v190
	v_exp_f32_e32 v191, v191
	v_exp_f32_e32 v192, v192
	v_exp_f32_e32 v193, v193
	v_exp_f32_e32 v194, v194
	v_exp_f32_e32 v195, v195
	v_exp_f32_e32 v196, v196
	v_exp_f32_e32 v197, v197
	v_pk_mul_f32 v[198:199], v[20:21], v[4:5]
	v_pk_mul_f32 v[200:201], v[22:23], v[6:7]
	v_pk_mul_f32 v[202:203], v[16:17], v[0:1]
	v_pk_mul_f32 v[204:205], v[18:19], v[2:3]
	v_pk_add_f32 v[190:191], v[190:191], v[188:189]
	v_pk_add_f32 v[192:193], v[192:193], v[188:189]
	v_pk_add_f32 v[194:195], v[194:195], v[188:189]
	v_pk_add_f32 v[196:197], v[196:197], v[188:189]
	v_rcp_f32_e32 v190, v190
	v_rcp_f32_e32 v191, v191
	v_rcp_f32_e32 v192, v192
	v_rcp_f32_e32 v193, v193
	v_rcp_f32_e32 v194, v194
	v_rcp_f32_e32 v195, v195
	v_rcp_f32_e32 v196, v196
	v_rcp_f32_e32 v197, v197
	v_pk_mul_f32 v[198:199], v[198:199], v[186:187] op_sel_hi:[1,0]
	v_pk_mul_f32 v[200:201], v[200:201], v[186:187] op_sel_hi:[1,0]
	v_pk_mul_f32 v[202:203], v[202:203], v[186:187] op_sel_hi:[1,0]
	v_pk_mul_f32 v[204:205], v[204:205], v[186:187] op_sel_hi:[1,0]
	v_pk_mul_f32 v[198:199], v[198:199], v[190:191]
	v_pk_mul_f32 v[200:201], v[200:201], v[192:193]
	v_pk_mul_f32 v[202:203], v[202:203], v[194:195]
	v_pk_mul_f32 v[204:205], v[204:205], v[196:197]
	v_cvt_pk_bf16_f32 v132, v198, v199
	v_cvt_pk_bf16_f32 v133, v200, v201
	v_cvt_pk_bf16_f32 v134, v202, v203
	v_cvt_pk_bf16_f32 v135, v204, v205
	s_mov_b64 s[6:7], 0
	flat_store_dwordx4 v[172:173], v[132:135]
